# early (conversion-first) group arrives at the P2->P4 barrier and starts its weight conversion immediately, waiting for the barrier only before attention; w_down split moved to 1152 items
# speedup vs baseline: 1.0035x; 1.0031x over previous
.Lgb3_wait:
	s_and_b32 s0, s2, 0x80
	s_cmp_lg_u32 s0, 0
	s_cbranch_scc1 .LBB0_317
	s_mov_b32 s1, 0

.Lcv_chain_wd:
	v_and_b32_e32 v110, 63, v252
	v_lshrrev_b32_e32 v0, 6, v252
	v_writelane_b32 v111, s16, 0
	v_writelane_b32 v111, s17, 1
	v_writelane_b32 v111, s18, 2
	v_writelane_b32 v111, s19, 3
	v_writelane_b32 v111, s20, 4
	v_writelane_b32 v111, s21, 5
	v_writelane_b32 v111, s22, 6
	v_writelane_b32 v111, s23, 7
	v_writelane_b32 v111, s24, 8
	v_writelane_b32 v111, s25, 9
	v_writelane_b32 v111, s26, 10
	v_writelane_b32 v111, s27, 11
	v_readfirstlane_b32 s0, v0
	s_mul_i32 s1, s0, 0x4100
	s_sub_i32 s16, s2, 0x80
	s_lshl_b32 s16, s16, 3
	s_add_u32 s16, s16, s0
	s_cmp_lt_u32 s16, 0x480
	s_cbranch_scc0 .Lcv_wde_skip
	v_lshrrev_b32_e32 v0, 4, v110
	v_and_b32_e32 v1, 15, v110
	v_and_b32_e32 v2, 7, v110
	v_lshrrev_b32_e32 v3, 3, v110
	v_mul_u32_u24_e32 v64, 0x2000, v0
	v_lshl_add_u32 v64, v1, 4, v64
	v_mul_u32_u24_e32 v65, 0x104, v0
	v_lshl_add_u32 v65, v1, 4, v65
	v_add_u32_e32 v65, s1, v65
	v_mul_u32_u24_e32 v66, 0x820, v2
	v_lshl_add_u32 v66, v3, 2, v66
	v_add_u32_e32 v66, s1, v66
	v_add_u32_e32 v67, 0x410, v66
	v_mul_u32_u24_e32 v68, 0x2c00, v3
	v_lshl_add_u32 v68, v2, 4, v68
	v_mov_b32_e32 v4, 0x23fa0
	ds_read_b64 v[0:1], v4
	s_waitcnt lgkmcnt(0)
	v_readfirstlane_b32 s18, v0
	v_readfirstlane_b32 s19, v1
	s_add_u32 s26, s54, 0x4800000
	s_addc_u32 s27, s55, 0
	s_nop 4
	s_lshr_b32 s98, s16, 5
	s_and_b32 s99, s16, 31
	s_lshl_b32 s0, s98, 19
	s_lshl_b32 s100, s99, 8
	s_add_u32 s0, s0, s100
	s_add_u32 s4, s18, s0
	s_addc_u32 s5, s19, 0
	s_mul_i32 s0, s99, 0xb0000
	s_lshl_b32 s100, s98, 7
	s_add_u32 s0, s0, s100
	s_add_u32 s24, s26, s0
	s_addc_u32 s25, s27, 0
	global_load_dwordx4 v[0:3], v64, s[4:5] nt
	s_add_u32 s4, s4, 0x8000
	s_addc_u32 s5, s5, 0
	global_load_dwordx4 v[4:7], v64, s[4:5] nt
	s_add_u32 s4, s4, 0x8000
	s_addc_u32 s5, s5, 0
	global_load_dwordx4 v[8:11], v64, s[4:5] nt
	s_add_u32 s4, s4, 0x8000
	s_addc_u32 s5, s5, 0
	global_load_dwordx4 v[12:15], v64, s[4:5] nt
	s_add_u32 s4, s4, 0x8000
	s_addc_u32 s5, s5, 0
	global_load_dwordx4 v[16:19], v64, s[4:5] nt
	s_add_u32 s4, s4, 0x8000
	s_addc_u32 s5, s5, 0
	global_load_dwordx4 v[20:23], v64, s[4:5] nt
	s_add_u32 s4, s4, 0x8000
	s_addc_u32 s5, s5, 0
	global_load_dwordx4 v[24:27], v64, s[4:5] nt
	s_add_u32 s4, s4, 0x8000
	s_addc_u32 s5, s5, 0
	global_load_dwordx4 v[28:31], v64, s[4:5] nt
	s_add_u32 s4, s4, 0x8000
	s_addc_u32 s5, s5, 0
	global_load_dwordx4 v[32:35], v64, s[4:5] nt
	s_add_u32 s4, s4, 0x8000
	s_addc_u32 s5, s5, 0
	global_load_dwordx4 v[36:39], v64, s[4:5] nt
	s_add_u32 s4, s4, 0x8000
	s_addc_u32 s5, s5, 0
	global_load_dwordx4 v[40:43], v64, s[4:5] nt
	s_add_u32 s4, s4, 0x8000
	s_addc_u32 s5, s5, 0
	global_load_dwordx4 v[44:47], v64, s[4:5] nt
	s_add_u32 s4, s4, 0x8000
	s_addc_u32 s5, s5, 0
	global_load_dwordx4 v[48:51], v64, s[4:5] nt
	s_add_u32 s4, s4, 0x8000
	s_addc_u32 s5, s5, 0
	global_load_dwordx4 v[52:55], v64, s[4:5] nt
	s_add_u32 s4, s4, 0x8000
	s_addc_u32 s5, s5, 0
	global_load_dwordx4 v[56:59], v64, s[4:5] nt
	s_add_u32 s4, s4, 0x8000
	s_addc_u32 s5, s5, 0
	global_load_dwordx4 v[60:63], v64, s[4:5] nt
	s_waitcnt vmcnt(0)
	s_branch .Lcv_wde_body

.Lcv_wde_body:
	s_mov_b32 s22, s24
	s_mov_b32 s23, s25
	v_mov_b32_e32 v69, v65
	ds_write2_b32 v69, v0, v1 offset1:1
	ds_write2_b32 v69, v2, v3 offset0:2 offset1:3
	v_add_u32_e32 v69, 0x410, v69
	ds_write2_b32 v69, v4, v5 offset1:1
	ds_write2_b32 v69, v6, v7 offset0:2 offset1:3
	v_add_u32_e32 v69, 0x410, v69
	ds_write2_b32 v69, v8, v9 offset1:1
	ds_write2_b32 v69, v10, v11 offset0:2 offset1:3
	v_add_u32_e32 v69, 0x410, v69
	ds_write2_b32 v69, v12, v13 offset1:1
	ds_write2_b32 v69, v14, v15 offset0:2 offset1:3
	v_add_u32_e32 v69, 0x410, v69
	ds_write2_b32 v69, v16, v17 offset1:1
	ds_write2_b32 v69, v18, v19 offset0:2 offset1:3
	v_add_u32_e32 v69, 0x410, v69
	ds_write2_b32 v69, v20, v21 offset1:1
	ds_write2_b32 v69, v22, v23 offset0:2 offset1:3
	v_add_u32_e32 v69, 0x410, v69
	ds_write2_b32 v69, v24, v25 offset1:1
	ds_write2_b32 v69, v26, v27 offset0:2 offset1:3
	v_add_u32_e32 v69, 0x410, v69
	ds_write2_b32 v69, v28, v29 offset1:1
	ds_write2_b32 v69, v30, v31 offset0:2 offset1:3
	v_add_u32_e32 v69, 0x410, v69
	ds_write2_b32 v69, v32, v33 offset1:1
	ds_write2_b32 v69, v34, v35 offset0:2 offset1:3
	v_add_u32_e32 v69, 0x410, v69
	ds_write2_b32 v69, v36, v37 offset1:1
	ds_write2_b32 v69, v38, v39 offset0:2 offset1:3
	v_add_u32_e32 v69, 0x410, v69
	ds_write2_b32 v69, v40, v41 offset1:1
	ds_write2_b32 v69, v42, v43 offset0:2 offset1:3
	v_add_u32_e32 v69, 0x410, v69
	ds_write2_b32 v69, v44, v45 offset1:1
	ds_write2_b32 v69, v46, v47 offset0:2 offset1:3
	v_add_u32_e32 v69, 0x410, v69
	ds_write2_b32 v69, v48, v49 offset1:1
	ds_write2_b32 v69, v50, v51 offset0:2 offset1:3
	v_add_u32_e32 v69, 0x410, v69
	ds_write2_b32 v69, v52, v53 offset1:1
	ds_write2_b32 v69, v54, v55 offset0:2 offset1:3
	v_add_u32_e32 v69, 0x410, v69
	ds_write2_b32 v69, v56, v57 offset1:1
	ds_write2_b32 v69, v58, v59 offset0:2 offset1:3
	v_add_u32_e32 v69, 0x410, v69
	ds_write2_b32 v69, v60, v61 offset1:1
	ds_write2_b32 v69, v62, v63 offset0:2 offset1:3
	s_waitcnt lgkmcnt(0)
	s_addk_i32 s16, 0x400
	s_cmp_lt_u32 s16, 0x480
	s_cbranch_scc0 .Lcv_wde_noload
	s_lshr_b32 s98, s16, 5
	s_and_b32 s99, s16, 31
	s_lshl_b32 s0, s98, 19
	s_lshl_b32 s100, s99, 8
	s_add_u32 s0, s0, s100
	s_add_u32 s4, s18, s0
	s_addc_u32 s5, s19, 0
	s_mul_i32 s0, s99, 0xb0000
	s_lshl_b32 s100, s98, 7
	s_add_u32 s0, s0, s100
	s_add_u32 s24, s26, s0
	s_addc_u32 s25, s27, 0
	global_load_dwordx4 v[0:3], v64, s[4:5] nt
	s_add_u32 s4, s4, 0x8000
	s_addc_u32 s5, s5, 0
	global_load_dwordx4 v[4:7], v64, s[4:5] nt
	s_add_u32 s4, s4, 0x8000
	s_addc_u32 s5, s5, 0
	global_load_dwordx4 v[8:11], v64, s[4:5] nt
	s_add_u32 s4, s4, 0x8000
	s_addc_u32 s5, s5, 0
	global_load_dwordx4 v[12:15], v64, s[4:5] nt
	s_add_u32 s4, s4, 0x8000
	s_addc_u32 s5, s5, 0
	global_load_dwordx4 v[16:19], v64, s[4:5] nt
	s_add_u32 s4, s4, 0x8000
	s_addc_u32 s5, s5, 0
	global_load_dwordx4 v[20:23], v64, s[4:5] nt
	s_add_u32 s4, s4, 0x8000
	s_addc_u32 s5, s5, 0
	global_load_dwordx4 v[24:27], v64, s[4:5] nt
	s_add_u32 s4, s4, 0x8000
	s_addc_u32 s5, s5, 0
	global_load_dwordx4 v[28:31], v64, s[4:5] nt
	s_add_u32 s4, s4, 0x8000
	s_addc_u32 s5, s5, 0
	global_load_dwordx4 v[32:35], v64, s[4:5] nt
	s_add_u32 s4, s4, 0x8000
	s_addc_u32 s5, s5, 0
	global_load_dwordx4 v[36:39], v64, s[4:5] nt
	s_add_u32 s4, s4, 0x8000
	s_addc_u32 s5, s5, 0
	global_load_dwordx4 v[40:43], v64, s[4:5] nt
	s_add_u32 s4, s4, 0x8000
	s_addc_u32 s5, s5, 0
	global_load_dwordx4 v[44:47], v64, s[4:5] nt
	s_add_u32 s4, s4, 0x8000
	s_addc_u32 s5, s5, 0
	global_load_dwordx4 v[48:51], v64, s[4:5] nt
	s_add_u32 s4, s4, 0x8000
	s_addc_u32 s5, s5, 0
	global_load_dwordx4 v[52:55], v64, s[4:5] nt
	s_add_u32 s4, s4, 0x8000
	s_addc_u32 s5, s5, 0
	global_load_dwordx4 v[56:59], v64, s[4:5] nt
	s_add_u32 s4, s4, 0x8000
	s_addc_u32 s5, s5, 0
	global_load_dwordx4 v[60:63], v64, s[4:5] nt
.Lcv_wde_noload:
	s_mov_b32 s8, s22
	s_mov_b32 s9, s23
	ds_read2_b32 v[70:71], v66 offset0:0 offset1:8
	ds_read2_b32 v[72:73], v66 offset0:65 offset1:73
	ds_read2_b32 v[74:75], v66 offset0:130 offset1:138
	ds_read2_b32 v[76:77], v66 offset0:195 offset1:203
	ds_read2_b32 v[78:79], v67 offset0:0 offset1:8
	ds_read2_b32 v[80:81], v67 offset0:65 offset1:73
	ds_read2_b32 v[82:83], v67 offset0:130 offset1:138
	ds_read2_b32 v[84:85], v67 offset0:195 offset1:203
	ds_read2_b32 v[86:87], v66 offset0:16 offset1:24
	ds_read2_b32 v[88:89], v66 offset0:81 offset1:89
	ds_read2_b32 v[90:91], v66 offset0:146 offset1:154
	ds_read2_b32 v[92:93], v66 offset0:211 offset1:219
	ds_read2_b32 v[94:95], v67 offset0:16 offset1:24
	ds_read2_b32 v[96:97], v67 offset0:81 offset1:89
	ds_read2_b32 v[98:99], v67 offset0:146 offset1:154
	ds_read2_b32 v[100:101], v67 offset0:211 offset1:219
	s_waitcnt lgkmcnt(8)
	v_cvt_pk_bf16_f32 v102, v70, v72
	v_cvt_pk_bf16_f32 v103, v74, v76
	v_cvt_pk_bf16_f32 v104, v78, v80
	v_cvt_pk_bf16_f32 v105, v82, v84
	v_cvt_pk_bf16_f32 v106, v71, v73
	v_cvt_pk_bf16_f32 v107, v75, v77
	v_cvt_pk_bf16_f32 v108, v79, v81
	v_cvt_pk_bf16_f32 v109, v83, v85
	global_store_dwordx4 v68, v[102:105], s[8:9]
	s_add_u32 s8, s8, 0x16000
	s_addc_u32 s9, s9, 0
	global_store_dwordx4 v68, v[106:109], s[8:9]
	s_add_u32 s8, s8, 0x16000
	s_addc_u32 s9, s9, 0
	ds_read2_b32 v[70:71], v66 offset0:32 offset1:40
	ds_read2_b32 v[72:73], v66 offset0:97 offset1:105
	ds_read2_b32 v[74:75], v66 offset0:162 offset1:170
	ds_read2_b32 v[76:77], v66 offset0:227 offset1:235
	ds_read2_b32 v[78:79], v67 offset0:32 offset1:40
	ds_read2_b32 v[80:81], v67 offset0:97 offset1:105
	ds_read2_b32 v[82:83], v67 offset0:162 offset1:170
	ds_read2_b32 v[84:85], v67 offset0:227 offset1:235
	s_waitcnt lgkmcnt(8)
	v_cvt_pk_bf16_f32 v102, v86, v88
	v_cvt_pk_bf16_f32 v103, v90, v92
	v_cvt_pk_bf16_f32 v104, v94, v96
	v_cvt_pk_bf16_f32 v105, v98, v100
	v_cvt_pk_bf16_f32 v106, v87, v89
	v_cvt_pk_bf16_f32 v107, v91, v93
	v_cvt_pk_bf16_f32 v108, v95, v97
	v_cvt_pk_bf16_f32 v109, v99, v101
	global_store_dwordx4 v68, v[102:105], s[8:9]
	s_add_u32 s8, s8, 0x16000
	s_addc_u32 s9, s9, 0
	global_store_dwordx4 v68, v[106:109], s[8:9]
	s_add_u32 s8, s8, 0x16000
	s_addc_u32 s9, s9, 0
	ds_read2_b32 v[86:87], v66 offset0:48 offset1:56
	ds_read2_b32 v[88:89], v66 offset0:113 offset1:121
	ds_read2_b32 v[90:91], v66 offset0:178 offset1:186
	ds_read2_b32 v[92:93], v66 offset0:243 offset1:251
	ds_read2_b32 v[94:95], v67 offset0:48 offset1:56
	ds_read2_b32 v[96:97], v67 offset0:113 offset1:121
	ds_read2_b32 v[98:99], v67 offset0:178 offset1:186
	ds_read2_b32 v[100:101], v67 offset0:243 offset1:251
	s_waitcnt lgkmcnt(8)
	v_cvt_pk_bf16_f32 v102, v70, v72
	v_cvt_pk_bf16_f32 v103, v74, v76
	v_cvt_pk_bf16_f32 v104, v78, v80
	v_cvt_pk_bf16_f32 v105, v82, v84
	v_cvt_pk_bf16_f32 v106, v71, v73
	v_cvt_pk_bf16_f32 v107, v75, v77
	v_cvt_pk_bf16_f32 v108, v79, v81
	v_cvt_pk_bf16_f32 v109, v83, v85
	global_store_dwordx4 v68, v[102:105], s[8:9]
	s_add_u32 s8, s8, 0x16000
	s_addc_u32 s9, s9, 0
	global_store_dwordx4 v68, v[106:109], s[8:9]
	s_add_u32 s8, s8, 0x16000
	s_addc_u32 s9, s9, 0
	s_waitcnt lgkmcnt(0)
	v_cvt_pk_bf16_f32 v102, v86, v88
	v_cvt_pk_bf16_f32 v103, v90, v92
	v_cvt_pk_bf16_f32 v104, v94, v96
	v_cvt_pk_bf16_f32 v105, v98, v100
	v_cvt_pk_bf16_f32 v106, v87, v89
	v_cvt_pk_bf16_f32 v107, v91, v93
	v_cvt_pk_bf16_f32 v108, v95, v97
	v_cvt_pk_bf16_f32 v109, v99, v101
	global_store_dwordx4 v68, v[102:105], s[8:9]
	s_add_u32 s8, s8, 0x16000
	s_addc_u32 s9, s9, 0
	global_store_dwordx4 v68, v[106:109], s[8:9]
	s_cmp_lt_u32 s16, 0x480
	s_cbranch_scc1 .Lcv_wde_top

.LBB0_325:
	s_mov_b64 s[4:5], exec
	v_readlane_b32 s0, v255, 1
	v_readlane_b32 s1, v255, 2
	s_and_b64 s[0:1], s[4:5], s[0:1]
	s_mov_b64 exec, s[0:1]
	s_cbranch_execz .Lgb3d_done
	v_mov_b32_e32 v0, 0x23fc4
	ds_read_b32 v1, v0
	s_waitcnt lgkmcnt(0)
	v_readfirstlane_b32 s9, v1
	s_mul_i32 s9, s9, 2
	v_mov_b32_e32 v0, 0x3000
	s_mov_b32 s1, 0

.LBB0_613:
	s_andn2_b64 vcc, exec, s[6:7]
	s_cbranch_vccnz .LBB0_618
	s_cmpk_gt_i32 s17, 0x7f
	s_cbranch_scc1 .LBB0_618
	v_and_b32_e32 v110, 63, v252
	v_lshrrev_b32_e32 v0, 6, v252
	v_writelane_b32 v111, s16, 0
	v_writelane_b32 v111, s17, 1
	v_writelane_b32 v111, s18, 2
	v_writelane_b32 v111, s19, 3
	v_writelane_b32 v111, s20, 4
	v_writelane_b32 v111, s21, 5
	v_writelane_b32 v111, s22, 6
	v_writelane_b32 v111, s23, 7
	v_writelane_b32 v111, s24, 8
	v_writelane_b32 v111, s25, 9
	v_writelane_b32 v111, s26, 10
	v_writelane_b32 v111, s27, 11
	v_readfirstlane_b32 s0, v0
	s_mul_i32 s1, s0, 0x4100
	s_lshl_b32 s16, s17, 3
	s_add_u32 s16, s16, s0
	s_add_u32 s16, s16, 0x480
	s_cmp_lt_u32 s16, 0xb00
	s_cbranch_scc0 .Lcv_wdl_skip
	v_lshrrev_b32_e32 v0, 4, v110
	v_and_b32_e32 v1, 15, v110
	v_and_b32_e32 v2, 7, v110
	v_lshrrev_b32_e32 v3, 3, v110
	v_mul_u32_u24_e32 v64, 0x2000, v0
	v_lshl_add_u32 v64, v1, 4, v64
	v_mul_u32_u24_e32 v65, 0x104, v0
	v_lshl_add_u32 v65, v1, 4, v65
	v_add_u32_e32 v65, s1, v65
	v_mul_u32_u24_e32 v66, 0x820, v2
	v_lshl_add_u32 v66, v3, 2, v66
	v_add_u32_e32 v66, s1, v66
	v_add_u32_e32 v67, 0x410, v66
	v_mul_u32_u24_e32 v68, 0x2c00, v3
	v_lshl_add_u32 v68, v2, 4, v68
	v_mov_b32_e32 v4, 0x23fa0
	ds_read_b64 v[0:1], v4
	s_waitcnt lgkmcnt(0)
	v_readfirstlane_b32 s18, v0
	v_readfirstlane_b32 s19, v1
	s_add_u32 s26, s54, 0x4800000
	s_addc_u32 s27, s55, 0
	s_nop 4
	s_lshr_b32 s98, s16, 5
	s_and_b32 s99, s16, 31
	s_lshl_b32 s0, s98, 19
	s_lshl_b32 s100, s99, 8
	s_add_u32 s0, s0, s100
	s_add_u32 s4, s18, s0
	s_addc_u32 s5, s19, 0
	s_mul_i32 s0, s99, 0xb0000
	s_lshl_b32 s100, s98, 7
	s_add_u32 s0, s0, s100
	s_add_u32 s24, s26, s0
	s_addc_u32 s25, s27, 0
	global_load_dwordx4 v[0:3], v64, s[4:5] nt
	s_add_u32 s4, s4, 0x8000
	s_addc_u32 s5, s5, 0
	global_load_dwordx4 v[4:7], v64, s[4:5] nt
	s_add_u32 s4, s4, 0x8000
	s_addc_u32 s5, s5, 0
	global_load_dwordx4 v[8:11], v64, s[4:5] nt
	s_add_u32 s4, s4, 0x8000
	s_addc_u32 s5, s5, 0
	global_load_dwordx4 v[12:15], v64, s[4:5] nt
	s_add_u32 s4, s4, 0x8000
	s_addc_u32 s5, s5, 0
	global_load_dwordx4 v[16:19], v64, s[4:5] nt
	s_add_u32 s4, s4, 0x8000
	s_addc_u32 s5, s5, 0
	global_load_dwordx4 v[20:23], v64, s[4:5] nt
	s_add_u32 s4, s4, 0x8000
	s_addc_u32 s5, s5, 0
	global_load_dwordx4 v[24:27], v64, s[4:5] nt
	s_add_u32 s4, s4, 0x8000
	s_addc_u32 s5, s5, 0
	global_load_dwordx4 v[28:31], v64, s[4:5] nt
	s_add_u32 s4, s4, 0x8000
	s_addc_u32 s5, s5, 0
	global_load_dwordx4 v[32:35], v64, s[4:5] nt
	s_add_u32 s4, s4, 0x8000
	s_addc_u32 s5, s5, 0
	global_load_dwordx4 v[36:39], v64, s[4:5] nt
	s_add_u32 s4, s4, 0x8000
	s_addc_u32 s5, s5, 0
	global_load_dwordx4 v[40:43], v64, s[4:5] nt
	s_add_u32 s4, s4, 0x8000
	s_addc_u32 s5, s5, 0
	global_load_dwordx4 v[44:47], v64, s[4:5] nt
	s_add_u32 s4, s4, 0x8000
	s_addc_u32 s5, s5, 0
	global_load_dwordx4 v[48:51], v64, s[4:5] nt
	s_add_u32 s4, s4, 0x8000
	s_addc_u32 s5, s5, 0
	global_load_dwordx4 v[52:55], v64, s[4:5] nt
	s_add_u32 s4, s4, 0x8000
	s_addc_u32 s5, s5, 0
	global_load_dwordx4 v[56:59], v64, s[4:5] nt
	s_add_u32 s4, s4, 0x8000
	s_addc_u32 s5, s5, 0
	global_load_dwordx4 v[60:63], v64, s[4:5] nt
	s_waitcnt vmcnt(0)
	s_branch .Lcv_wdl_body
